# baseline (speedup 1.0000x reference)
.LBB0_857:
	s_or_b64 exec, exec, s[48:49]
	s_add_i32 s74, s74, 1
	s_xor_b64 s[82:83], s[82:83], -1
	s_cmp_lg_u32 s74, s33
	s_cbranch_scc0 .LBB0_782
	s_branch .Lnb_top

.Lnb_top:
	s_and_saveexec_b64 s[48:49], s[2:3]
	s_cbranch_execz .LBB0_865
	v_mov_b32_e32 v9, 0
	s_and_saveexec_b64 s[50:51], s[78:79]
	s_cbranch_execz .LBB0_863
	v_cndmask_b32_e64 v8, 0, 1, s[82:83]
	v_lshl_add_u32 v8, v8, 10, v157
	ds_read_b32 v11, v8
	ds_read_b32 v12, v8 offset:256
	ds_read_b32 v13, v8 offset:512
	v_mov_b32_e32 v9, 0
	v_cmp_lt_u32_e64 s[34:35], 1, v125
	v_cmp_lt_u32_e64 s[52:53], 2, v125
	s_waitcnt lgkmcnt(0)
	v_add_f32_e32 v9, v9, v11
	v_add_f32_e32 v12, v9, v12
	v_cndmask_b32_e64 v9, v9, v12, s[34:35]
	v_add_f32_e32 v13, v9, v13
	v_cndmask_b32_e64 v9, v9, v13, s[52:53]

.LBB0_961:
	s_or_b64 exec, exec, s[34:35]
	s_waitcnt lgkmcnt(0)
	s_barrier
	v_add_u32_e32 v16, s63, v145
	v_add_u32_e32 v20, v146, v149
	v_add_u32_e32 v21, v147, v149
	ds_read_b128 v[228:231], v16
	ds_read_b128 v[232:235], v181
	ds_read_b128 v[236:239], v20
	ds_read_b128 v[240:243], v21
	s_and_saveexec_b64 s[34:35], s[90:91]
	s_cbranch_execz .LBB0_963
	ds_read_b128 v[16:19], v176 offset:44544
	v_add_u32_e32 v20, v144, v149
	ds_read_b128 v[20:23], v20
	s_waitcnt lgkmcnt(0)
	v_mfma_f32_16x16x32_bf16 v[12:15], v[16:19], v[20:23], v[12:15]
	s_nop 7
	ds_write_b32 v177, v12 offset:18944
	ds_write_b32 v178, v13 offset:18944
	ds_write_b32 v179, v14 offset:18944
	ds_write_b32 v180, v15 offset:18944
	v_add_u32_e32 v12, v144, v150
	ds_read_b128 v[12:15], v12
	s_waitcnt lgkmcnt(0)
	v_mfma_f32_16x16x32_bf16 v[8:11], v[16:19], v[12:15], v[8:11]
	s_nop 7
	ds_write_b32 v177, v8 offset:19008
	ds_write_b32 v178, v9 offset:19008
	ds_write_b32 v179, v10 offset:19008
	ds_write_b32 v180, v11 offset:19008
.LBB0_963:
	s_or_b64 exec, exec, s[34:35]
	s_waitcnt lgkmcnt(0)
	v_mfma_f32_16x16x32_bf16 v[0:3], v[228:231], v[236:239], v[0:3]
	ds_read_b32 v16, v151 offset:16640
	s_and_b64 s[34:35], s[48:49], exec
	s_cselect_b32 s48, 0x4000, s8
	s_waitcnt lgkmcnt(1)
	v_mfma_f32_16x16x32_bf16 v[0:3], v[232:235], v[240:243], v[0:3]
	v_add_u32_e32 v20, v147, v152
	s_cselect_b32 s51, 0, 0x17400
	ds_read_b128 v[20:23], v20
	s_cselect_b32 s50, 0x2000, s97
	s_add_i32 s62, s62, s77
	s_waitcnt lgkmcnt(1)
	s_nop 1
	v_pk_mul_f32 v[2:3], v[2:3], v[16:17] op_sel_hi:[1,0]
	v_pk_mul_f32 v[0:1], v[0:1], v[16:17] op_sel_hi:[1,0]
	v_add_u32_e32 v16, v146, v152
	ds_read_b128 v[16:19], v16
	s_waitcnt lgkmcnt(0)
	v_mfma_f32_16x16x32_bf16 v[4:7], v[228:231], v[16:19], v[4:7]
	ds_read_b32 v8, v153 offset:16640
	s_waitcnt lgkmcnt(0)
	s_barrier
	v_mfma_f32_16x16x32_bf16 v[4:7], v[232:235], v[20:23], v[4:7]
	s_nop 7
	v_pk_mul_f32 v[6:7], v[6:7], v[8:9] op_sel_hi:[1,0]
	v_pk_mul_f32 v[4:5], v[4:5], v[8:9] op_sel_hi:[1,0]
	v_cvt_pk_bf16_f32 v8, v0, s0
	ds_write_b16 v123, v8
	v_cvt_pk_bf16_f32 v8, v1, s0
	ds_write_b16 v123, v8 offset:144
	v_cvt_pk_bf16_f32 v8, v2, s0
	ds_write_b16 v123, v8 offset:288
	v_cvt_pk_bf16_f32 v8, v3, s0
	ds_write_b16 v123, v8 offset:432
	v_cvt_pk_bf16_f32 v8, v4, s0
	ds_write_b16 v124, v8
	v_cvt_pk_bf16_f32 v8, v5, s0
	ds_write_b16 v124, v8 offset:144
	v_cvt_pk_bf16_f32 v8, v6, s0
	ds_write_b16 v124, v8 offset:288
	v_cvt_pk_bf16_f32 v8, v7, s0
	ds_write_b16 v124, v8 offset:432
	ds_read2st64_b32 v[10:11], v182 offset0:74 offset1:75
	ds_read2st64_b32 v[8:9], v182 offset0:76 offset1:77
	s_waitcnt lgkmcnt(1)
	v_mov_b32_e32 v12, v11
	s_waitcnt lgkmcnt(0)
	v_lshl_add_u32 v243, v148, 2, s48
	ds_read_b32 v228, v243
	ds_read_b32 v229, v243 offset:4
	ds_read_b32 v230, v243 offset:8
	ds_read_b32 v231, v243 offset:12
	v_add_u32_e32 v243, s51, v183
	ds_read_b32 v232, v243
	v_add_u32_e32 v243, s51, v184
	ds_read_b32 v233, v243
	v_add_u32_e32 v243, s51, v185
	ds_read_b32 v234, v243
	v_add_u32_e32 v243, s51, v186
	ds_read_b32 v235, v243
	v_add_u32_e32 v243, s50, v183
	ds_read_b32 v236, v243
	v_add_u32_e32 v243, s50, v184
	ds_read_b32 v237, v243
	v_add_u32_e32 v243, s50, v185
	ds_read_b32 v238, v243
	v_add_u32_e32 v243, s50, v186
	ds_read_b32 v239, v243
	v_mov_b32_e32 v13, v9
	v_mov_b32_e32 v14, v10
	v_mov_b32_e32 v15, v8
	s_nop 1
	v_add_f32_dpp v14, v14, v14 quad_perm:[1,0,3,2] row_mask:0xf bank_mask:0xf
	v_add_f32_dpp v12, v12, v12 quad_perm:[1,0,3,2] row_mask:0xf bank_mask:0xf
	v_add_f32_dpp v15, v15, v15 quad_perm:[1,0,3,2] row_mask:0xf bank_mask:0xf
	v_add_f32_dpp v13, v13, v13 quad_perm:[1,0,3,2] row_mask:0xf bank_mask:0xf
	v_add_f32_dpp v14, v14, v14 quad_perm:[2,3,0,1] row_mask:0xf bank_mask:0xf
	v_add_f32_dpp v12, v12, v12 quad_perm:[2,3,0,1] row_mask:0xf bank_mask:0xf
	v_add_f32_dpp v15, v15, v15 quad_perm:[2,3,0,1] row_mask:0xf bank_mask:0xf
	v_add_f32_dpp v13, v13, v13 quad_perm:[2,3,0,1] row_mask:0xf bank_mask:0xf
	v_add_f32_dpp v14, v14, v14 row_half_mirror row_mask:0xf bank_mask:0xf
	v_add_f32_dpp v12, v12, v12 row_half_mirror row_mask:0xf bank_mask:0xf
	v_add_f32_dpp v15, v15, v15 row_half_mirror row_mask:0xf bank_mask:0xf
	v_add_f32_dpp v13, v13, v13 row_half_mirror row_mask:0xf bank_mask:0xf
	v_add_f32_dpp v14, v14, v14 row_mirror row_mask:0xf bank_mask:0xf
	v_add_f32_dpp v12, v12, v12 row_mirror row_mask:0xf bank_mask:0xf
	v_add_f32_dpp v15, v15, v15 row_mirror row_mask:0xf bank_mask:0xf
	v_add_f32_dpp v13, v13, v13 row_mirror row_mask:0xf bank_mask:0xf
	v_add_f32_dpp v14, v14, v14 row_bcast:15 row_mask:0xa bank_mask:0xf
	v_add_f32_dpp v12, v12, v12 row_bcast:15 row_mask:0xa bank_mask:0xf
	v_add_f32_dpp v15, v15, v15 row_bcast:15 row_mask:0xa bank_mask:0xf
	v_add_f32_dpp v13, v13, v13 row_bcast:15 row_mask:0xa bank_mask:0xf
	v_add_f32_dpp v14, v14, v14 row_bcast:31 row_mask:0xc bank_mask:0xf
	v_add_f32_dpp v12, v12, v12 row_bcast:31 row_mask:0xc bank_mask:0xf
	v_add_f32_dpp v15, v15, v15 row_bcast:31 row_mask:0xc bank_mask:0xf
	v_add_f32_dpp v13, v13, v13 row_bcast:31 row_mask:0xc bank_mask:0xf
	s_nop 1

	s_nop 0
	v_readlane_b32 s34, v14, 63
	v_readlane_b32 s35, v12, 63
	v_readlane_b32 s49, v15, 63
	v_readlane_b32 s52, v13, 63
	v_fma_f32 v12, s34, v111, v10
	v_fmac_f32_e32 v11, s35, v111
	v_fma_f32 v10, s49, v111, v8
	v_fmac_f32_e32 v9, s52, v111
	v_mul_f32_e32 v8, v12, v12
	v_mul_f32_e32 v13, v11, v11
	v_mul_f32_e32 v14, v10, v10
	v_mul_f32_e32 v15, v9, v9
	s_nop 1
	v_add_f32_dpp v8, v8, v8 quad_perm:[1,0,3,2] row_mask:0xf bank_mask:0xf
	v_add_f32_dpp v13, v13, v13 quad_perm:[1,0,3,2] row_mask:0xf bank_mask:0xf
	v_add_f32_dpp v14, v14, v14 quad_perm:[1,0,3,2] row_mask:0xf bank_mask:0xf
	v_add_f32_dpp v15, v15, v15 quad_perm:[1,0,3,2] row_mask:0xf bank_mask:0xf
	v_add_f32_dpp v8, v8, v8 quad_perm:[2,3,0,1] row_mask:0xf bank_mask:0xf
	v_add_f32_dpp v13, v13, v13 quad_perm:[2,3,0,1] row_mask:0xf bank_mask:0xf
	v_add_f32_dpp v14, v14, v14 quad_perm:[2,3,0,1] row_mask:0xf bank_mask:0xf
	v_add_f32_dpp v15, v15, v15 quad_perm:[2,3,0,1] row_mask:0xf bank_mask:0xf
	v_add_f32_dpp v8, v8, v8 row_half_mirror row_mask:0xf bank_mask:0xf
	v_add_f32_dpp v13, v13, v13 row_half_mirror row_mask:0xf bank_mask:0xf
	v_add_f32_dpp v14, v14, v14 row_half_mirror row_mask:0xf bank_mask:0xf
	v_add_f32_dpp v15, v15, v15 row_half_mirror row_mask:0xf bank_mask:0xf
	v_add_f32_dpp v8, v8, v8 row_mirror row_mask:0xf bank_mask:0xf
	v_add_f32_dpp v13, v13, v13 row_mirror row_mask:0xf bank_mask:0xf
	v_add_f32_dpp v14, v14, v14 row_mirror row_mask:0xf bank_mask:0xf
	v_add_f32_dpp v15, v15, v15 row_mirror row_mask:0xf bank_mask:0xf
	v_add_f32_dpp v8, v8, v8 row_bcast:15 row_mask:0xa bank_mask:0xf
	v_add_f32_dpp v13, v13, v13 row_bcast:15 row_mask:0xa bank_mask:0xf
	v_add_f32_dpp v14, v14, v14 row_bcast:15 row_mask:0xa bank_mask:0xf
	v_add_f32_dpp v15, v15, v15 row_bcast:15 row_mask:0xa bank_mask:0xf
	v_add_f32_dpp v8, v8, v8 row_bcast:31 row_mask:0xc bank_mask:0xf
	v_add_f32_dpp v13, v13, v13 row_bcast:31 row_mask:0xc bank_mask:0xf
	v_add_f32_dpp v14, v14, v14 row_bcast:31 row_mask:0xc bank_mask:0xf
	v_add_f32_dpp v15, v15, v15 row_bcast:31 row_mask:0xc bank_mask:0xf
	s_nop 1

	v_cmp_gt_i32_e64 s[34:35], s75, v148
	v_readlane_b32 s55, v8, 63
	v_readlane_b32 s54, v13, 63
	v_readlane_b32 s53, v14, 63
	v_readlane_b32 s52, v15, 63
	v_lshl_add_u32 v8, v148, 2, s48
	s_waitcnt lgkmcnt(0)
	s_and_saveexec_b64 s[48:49], s[34:35]
	s_cbranch_execz .LBB0_967
	v_fma_f32 v13, s55, v112, v27
	v_cmp_gt_f32_e64 s[34:35], s76, v13
	v_mul_f32_e32 v14, 0x4b800000, v13
	v_mov_b32_e32 v29, v228
	v_cndmask_b32_e64 v13, v13, v14, s[34:35]
	v_rsq_f32_e32 v13, v13
	s_nop 0
	v_mul_f32_e32 v14, 0x45800000, v13
	v_cndmask_b32_e64 v13, v13, v14, s[34:35]
	v_mul_f32_e32 v12, v12, v13
	v_mov_b32_e32 v13, v232
	v_pk_mul_f32 v[12:13], v[28:29], v[12:13]
	s_nop 0
	v_add_f32_e32 v12, v119, v12
	v_add_f32_e32 v12, v12, v13
	v_mov_b32_e32 v13, v236
	v_mul_f32_e32 v12, v13, v12
	v_cvt_pk_bf16_f32 v14, v12, s0
	v_add_u32_e32 v12, s62, v148
	v_ashrrev_i32_e32 v13, 31, v12
	v_lshlrev_b64 v[12:13], 13, v[12:13]
	v_lshl_add_u64 v[12:13], v[32:33], 0, v[12:13]
	global_store_short v[12:13], v14, off
	s_or_b64 exec, exec, s[48:49]
	v_cmp_gt_i32_e64 s[34:35], s75, v154
	s_and_saveexec_b64 s[48:49], s[34:35]
	s_cbranch_execnz .LBB0_968
